# candL + intra-CU stagger of the 4 cache-stream waves (wave w enters the far-rows loop w x 0.33 us late)
# baseline (speedup 1.0000x reference)
; __device__ __forceinline__ float bf_lo(unsigned w) { return __uint_as_float(w << 16); }
; __device__ __forceinline__ float bf_hi(unsigned w) { return __uint_as_float(w & 0xffff0000u); }
; __device__ __forceinline__ float alibi_slope(int h) { return exp2f(-(float)(h + 1)); }
; __device__ __forceinline__ float row_sum_f(float v) { v += dpp_f<0x128>(v); v += dpp_f<0x124>(v); v += dpp_f<0x122>(v); v += dpp_f<0x121>(v); return v; }
; __device__ __forceinline__ void stream_task(const Args& a, const int task, const int wave, const float kbA, LAS unsigned* rb, unsigned& ep) {
;     ...
;             const int b = task >> 1, hh = task & 1, hd = 4 * hh + (lane >> 4), dl = 4 * (lane & 15);
;             const float slope2 = alibi_slope(hd) * LOG2E;
;             f32x4 q[8], O[8]; float M[8], l[8];
; #pragma unroll
;             for (int i = 0; i < 8; ++i) {
;                 const u32x2 qr = *(const u32x2*)(QA + (size_t)(NTP + b * DS + i) * 512 + hd * 64 + dl);
;                 q[i] = (f32x4){bf_lo(qr.x), bf_hi(qr.x), bf_lo(qr.y), bf_hi(qr.y)};
;                 M[i] = sqrtf(row_sum_f(q[i][0] * q[i][0] + q[i][1] * q[i][1] + q[i][2] * q[i][2] + q[i][3] * q[i][3])) * kbA;
;                 O[i] = (f32x4){0.f, 0.f, 0.f, 0.f}; l[i] = 0.f;
;             }
;             const f32x4 qa = wave == 0 ? q[0] : wave == 1 ? q[1] : wave == 2 ? q[2] : q[3], qb = wave == 0 ? q[4] : wave == 1 ? q[5] : wave == 2 ? q[6] : q[7];
;             const float Ma = wave == 0 ? M[0] : wave == 1 ? M[1] : wave == 2 ? M[2] : M[3], Mb = wave == 0 ? M[4] : wave == 1 ? M[5] : wave == 2 ? M[6] : M[7];
;             f32x4 Oa = {0.f, 0.f, 0.f, 0.f}, Ob = {0.f, 0.f, 0.f, 0.f}; float la = 0.f, lb = 0.f;
.LBB0_1138:
	v_lshlrev_b32_e32 v183, 6, v6
	v_add_u32_e32 v6, 1, v6
	v_cvt_f32_ubyte0_e32 v6, v6
	s_mov_b32 s0, 0x42fc0000
	v_cmp_lt_f32_e32 vcc, s0, v6
	v_add_f32_e32 v7, v7, v8
	v_mul_f32_e32 v8, 0x4f800000, v7
	v_cndmask_b32_e32 v27, 0, v181, vcc
	v_sub_f32_e32 v6, v27, v6
	v_cndmask_b32_e32 v27, 0, v182, vcc
	v_cmp_gt_f32_e32 vcc, s34, v7
	v_exp_f32_e32 v6, v6
	s_ashr_i32 s19, s18, 31
	v_cndmask_b32_e32 v7, v7, v8, vcc
	v_sqrt_f32_e32 v8, v7
	v_ldexp_f32 v6, v6, v27
	v_mul_f32_e32 v184, 0x3fb8aa3b, v6
	v_cndmask_b32_e64 v6, v132, v122, s[8:9]
	v_add_u32_e32 v27, -1, v8
	v_fma_f32 v28, -v27, v8, v7
	v_cmp_ge_f32_e64 s[16:17], 0, v28
	v_add_u32_e32 v28, 1, v8
	v_cndmask_b32_e64 v150, v6, v23, s[12:13]
	v_cndmask_b32_e64 v27, v8, v27, s[16:17]
	v_fma_f32 v8, -v28, v8, v7
	v_cmp_lt_f32_e64 s[16:17], 0, v8
	v_mov_b32_e32 v68, v67
	v_mov_b32_e32 v69, v67
	v_cndmask_b32_e64 v8, v27, v28, s[16:17]
	v_mul_f32_e32 v27, 0x37800000, v8
	v_cndmask_b32_e32 v8, v8, v27, vcc
	v_cmp_class_f32_e32 vcc, v7, v180
	v_readlane_b32 s0, v240, 18
	v_mov_b32_e32 v66, v67
	v_cndmask_b32_e32 v7, v8, v7, vcc
	v_mul_f32_e32 v191, v1, v7
	v_add_f32_e32 v7, v9, v10
	v_cmp_gt_f32_e32 vcc, s34, v7
	v_mul_f32_e32 v8, 0x4f800000, v7
	v_mov_b64_e32 v[74:75], v[68:69]
	v_cndmask_b32_e32 v7, v7, v8, vcc
	v_sqrt_f32_e32 v8, v7
	v_readlane_b32 s1, v240, 19
	v_mov_b64_e32 v[72:73], v[66:67]
	v_mov_b64_e32 v[70:71], v[68:69]
	v_add_u32_e32 v9, -1, v8
	v_fma_f32 v10, -v9, v8, v7
	v_cmp_ge_f32_e64 s[16:17], 0, v10
	v_add_u32_e32 v10, 1, v8
	s_mov_b32 s2, 0
	v_cndmask_b32_e64 v9, v8, v9, s[16:17]
	v_fma_f32 v8, -v10, v8, v7
	v_cmp_lt_f32_e64 s[16:17], 0, v8
	v_mov_b32_e32 v189, 0
	v_mov_b64_e32 v[68:69], v[66:67]
	v_cndmask_b32_e64 v8, v9, v10, s[16:17]
	v_mul_f32_e32 v9, 0x37800000, v8
	v_cndmask_b32_e32 v8, v8, v9, vcc
	v_cmp_class_f32_e32 vcc, v7, v180
	v_mov_b32_e32 v188, 0
	s_nop 0
	v_cndmask_b32_e32 v7, v8, v7, vcc
	v_mul_f32_e32 v190, v1, v7
	v_add_f32_e32 v7, v11, v12
	v_cmp_gt_f32_e32 vcc, s34, v7
	v_mul_f32_e32 v8, 0x4f800000, v7
	s_nop 0
	v_cndmask_b32_e32 v7, v7, v8, vcc
	v_sqrt_f32_e32 v8, v7
	s_nop 0
	v_add_u32_e32 v9, -1, v8
	v_fma_f32 v10, -v9, v8, v7
	v_cmp_ge_f32_e64 s[16:17], 0, v10
	v_add_u32_e32 v10, 1, v8
	s_nop 0
	v_cndmask_b32_e64 v9, v8, v9, s[16:17]
	v_fma_f32 v8, -v10, v8, v7
	v_cmp_lt_f32_e64 s[16:17], 0, v8
	s_nop 1
	v_cndmask_b32_e64 v8, v9, v10, s[16:17]
	v_mul_f32_e32 v9, 0x37800000, v8
	v_cndmask_b32_e32 v8, v8, v9, vcc
	v_cmp_class_f32_e32 vcc, v7, v180
	s_nop 1
	v_cndmask_b32_e32 v7, v8, v7, vcc
	v_mul_f32_e32 v157, v1, v7
	v_add_f32_e32 v7, v13, v14
	v_cmp_gt_f32_e32 vcc, s34, v7
	v_mul_f32_e32 v8, 0x4f800000, v7
	s_nop 0
	v_cndmask_b32_e32 v7, v7, v8, vcc
	v_sqrt_f32_e32 v8, v7
	s_nop 0
	v_add_u32_e32 v9, -1, v8
	v_fma_f32 v10, -v9, v8, v7
	v_cmp_ge_f32_e64 s[16:17], 0, v10
	v_add_u32_e32 v10, 1, v8
	s_nop 0
	v_cndmask_b32_e64 v9, v8, v9, s[16:17]
	v_fma_f32 v8, -v10, v8, v7
	v_cmp_lt_f32_e64 s[16:17], 0, v8
	s_nop 1
	v_cndmask_b32_e64 v8, v9, v10, s[16:17]
	v_mul_f32_e32 v9, 0x37800000, v8
	v_cndmask_b32_e32 v8, v8, v9, vcc
	v_cmp_class_f32_e32 vcc, v7, v180
	s_nop 1
	v_cndmask_b32_e32 v7, v8, v7, vcc
	v_mul_f32_e32 v156, v1, v7
	v_add_f32_e32 v7, v15, v16
	v_cmp_gt_f32_e32 vcc, s34, v7
	v_mul_f32_e32 v8, 0x4f800000, v7
	v_cndmask_b32_e64 v6, v156, v157, s[8:9]
	v_cndmask_b32_e32 v7, v7, v8, vcc
	v_sqrt_f32_e32 v8, v7
	v_cndmask_b32_e64 v6, v6, v190, s[6:7]
	v_cndmask_b32_e64 v114, v6, v191, s[4:5]
	v_add_u32_e32 v9, -1, v8
	v_fma_f32 v10, -v9, v8, v7
	v_cmp_ge_f32_e64 s[16:17], 0, v10
	v_add_u32_e32 v10, 1, v8
	s_nop 0
	v_cndmask_b32_e64 v9, v8, v9, s[16:17]
	v_fma_f32 v8, -v10, v8, v7
	v_cmp_lt_f32_e64 s[16:17], 0, v8
	s_nop 1
; __device__ __forceinline__ float row_sum_f(float v) { v += dpp_f<0x128>(v); v += dpp_f<0x124>(v); v += dpp_f<0x122>(v); v += dpp_f<0x121>(v); return v; }
; __device__ __forceinline__ void stream_task(const Args& a, const int task, const int wave, const float kbA, LAS unsigned* rb, unsigned& ep) {
;     ...
;                 M[i] = sqrtf(row_sum_f(q[i][0] * q[i][0] + q[i][1] * q[i][1] + q[i][2] * q[i][2] + q[i][3] * q[i][3])) * kbA;
;                 O[i] = (f32x4){0.f, 0.f, 0.f, 0.f}; l[i] = 0.f;
;             }
;             const f32x4 qa = wave == 0 ? q[0] : wave == 1 ? q[1] : wave == 2 ? q[2] : q[3], qb = wave == 0 ? q[4] : wave == 1 ? q[5] : wave == 2 ? q[6] : q[7];
;             const float Ma = wave == 0 ? M[0] : wave == 1 ? M[1] : wave == 2 ? M[2] : M[3], Mb = wave == 0 ? M[4] : wave == 1 ? M[5] : wave == 2 ? M[6] : M[7];
;             f32x4 Oa = {0.f, 0.f, 0.f, 0.f}, Ob = {0.f, 0.f, 0.f, 0.f}; float la = 0.f, lb = 0.f;
;             const size_t co = ((size_t)b * LA * 8 + hd) * 64 + dl;
;             const float* kc = a.in[2] + co; const float* vc = a.in[3] + co; float* ko = out + O_AKS + co; float* vo = out + O_AVS + co;
;             constexpr int NGRP = 480 / SB;
;             int gq = 0;
;             f32x4 k4[SB], v4[SB];
; #pragma unroll
;             for (int u = 0; u < SB; ++u) { const size_t ro = (size_t)(wave + 4 * (SB * gq + u)) * 512; k4[u] = __builtin_nontemporal_load((const f32x4*)(kc + ro)); v4[u] = __builtin_nontemporal_load((const f32x4*)(vc + ro)); }
	v_cndmask_b32_e64 v8, v9, v10, s[16:17]
	v_mul_f32_e32 v9, 0x37800000, v8
	v_cndmask_b32_e32 v8, v8, v9, vcc
	v_cmp_class_f32_e32 vcc, v7, v180
	s_nop 1
	v_cndmask_b32_e32 v7, v8, v7, vcc
	v_mul_f32_e32 v187, v1, v7
	v_add_f32_e32 v7, v17, v18
	v_cmp_gt_f32_e32 vcc, s34, v7
	v_mul_f32_e32 v8, 0x4f800000, v7
	s_nop 0
	v_cndmask_b32_e32 v7, v7, v8, vcc
	v_sqrt_f32_e32 v8, v7
	s_nop 0
	v_add_u32_e32 v9, -1, v8
	v_fma_f32 v10, -v9, v8, v7
	v_cmp_ge_f32_e64 s[16:17], 0, v10
	v_add_u32_e32 v10, 1, v8
	s_nop 0
	v_cndmask_b32_e64 v9, v8, v9, s[16:17]
	v_fma_f32 v8, -v10, v8, v7
	v_cmp_lt_f32_e64 s[16:17], 0, v8
	s_nop 1
	v_cndmask_b32_e64 v8, v9, v10, s[16:17]
	v_mul_f32_e32 v9, 0x37800000, v8
	v_cndmask_b32_e32 v8, v8, v9, vcc
	v_cmp_class_f32_e32 vcc, v7, v180
	s_nop 1
	v_cndmask_b32_e32 v7, v8, v7, vcc
	v_mul_f32_e32 v186, v1, v7
	v_add_f32_e32 v7, v19, v20
	v_cmp_gt_f32_e32 vcc, s34, v7
	v_mul_f32_e32 v8, 0x4f800000, v7
	s_nop 0
	v_cndmask_b32_e32 v7, v7, v8, vcc
	v_sqrt_f32_e32 v8, v7
	s_nop 0
	v_add_u32_e32 v9, -1, v8
	v_fma_f32 v10, -v9, v8, v7
	v_cmp_ge_f32_e64 s[16:17], 0, v10
	v_add_u32_e32 v10, 1, v8
	s_nop 0
	v_cndmask_b32_e64 v9, v8, v9, s[16:17]
	v_fma_f32 v8, -v10, v8, v7
	v_cmp_lt_f32_e64 s[16:17], 0, v8
	s_nop 1
	v_cndmask_b32_e64 v8, v9, v10, s[16:17]
	v_mul_f32_e32 v9, 0x37800000, v8
	v_cndmask_b32_e32 v8, v8, v9, vcc
	v_cmp_class_f32_e32 vcc, v7, v180
	s_nop 1
	v_cndmask_b32_e32 v7, v8, v7, vcc
	v_mul_f32_e32 v185, v1, v7
	v_add_f32_e32 v7, v21, v22
	v_cmp_gt_f32_e32 vcc, s34, v7
	v_mul_f32_e32 v8, 0x4f800000, v7
	s_nop 0
	v_cndmask_b32_e32 v7, v7, v8, vcc
	v_sqrt_f32_e32 v8, v7
	s_nop 0
	v_add_u32_e32 v9, -1, v8
	v_fma_f32 v10, -v9, v8, v7
	v_cmp_ge_f32_e64 s[16:17], 0, v10
	v_add_u32_e32 v10, 1, v8
	s_nop 0
	v_cndmask_b32_e64 v9, v8, v9, s[16:17]
	v_fma_f32 v8, -v10, v8, v7
	v_cmp_lt_f32_e64 s[16:17], 0, v8
	s_nop 1
	v_cndmask_b32_e64 v8, v9, v10, s[16:17]
	v_mul_f32_e32 v9, 0x37800000, v8
	v_cndmask_b32_e32 v8, v8, v9, vcc
	v_cmp_class_f32_e32 vcc, v7, v180
	s_lshl_b64 s[16:17], s[18:19], 20
	v_cndmask_b32_e64 v9, v135, v121, s[8:9]
	v_cndmask_b32_e32 v7, v8, v7, vcc
	v_mul_f32_e32 v91, v1, v7
	v_cndmask_b32_e64 v6, v91, v185, s[8:9]
	v_cndmask_b32_e64 v7, v133, v123, s[8:9]
	v_cndmask_b32_e64 v6, v6, v186, s[6:7]
	v_cndmask_b32_e64 v151, v7, v24, s[12:13]
	v_cndmask_b32_e64 v192, v6, v187, s[4:5]
	v_or3_b32 v7, s17, 0, 0
	v_or3_b32 v6, s16, v183, v92
	v_lshlrev_b64 v[30:31], 2, v[6:7]
	v_lshl_add_u64 v[152:153], s[40:41], 0, v[30:31]
	v_lshl_add_u64 v[154:155], s[42:43], 0, v[30:31]
	v_lshl_add_u64 v[6:7], v[152:153], 0, s[72:73]
	global_load_dwordx4 v[84:87], v[6:7], off nt
	v_lshl_add_u64 v[6:7], v[154:155], 0, s[72:73]
	global_load_dwordx4 v[80:83], v[6:7], off nt
	v_lshl_add_u64 v[6:7], v[152:153], 0, s[74:75]
	v_cndmask_b32_e64 v8, v134, v120, s[8:9]
	v_cndmask_b32_e64 v149, v9, v26, s[12:13]
	global_load_dwordx4 v[26:29], v[6:7], off nt
	v_lshl_add_u64 v[6:7], v[154:155], 0, s[74:75]
	v_cndmask_b32_e64 v148, v8, v25, s[12:13]
	global_load_dwordx4 v[22:25], v[6:7], off nt
	v_lshl_add_u64 v[6:7], v[152:153], 0, s[76:77]
	global_load_dwordx4 v[18:21], v[6:7], off nt
	v_lshl_add_u64 v[6:7], v[154:155], 0, s[76:77]
	global_load_dwordx4 v[14:17], v[6:7], off nt
	v_lshl_add_u64 v[6:7], v[152:153], 0, s[78:79]
	global_load_dwordx4 v[10:13], v[6:7], off nt
	v_lshl_add_u64 v[6:7], v[154:155], 0, s[78:79]
	global_load_dwordx4 v[6:9], v[6:7], off nt
	v_lshl_add_u64 v[146:147], s[0:1], 0, v[30:31]
	v_lshl_add_u64 v[144:145], s[64:65], 0, v[30:31]
	s_mov_b32 s0, s3
.Lstag_s_loop:
	s_cmp_eq_u32 s0, 0
	s_cbranch_scc1 .Lstag_s_done
	s_sleep 12
	s_sub_u32 s0, s0, 1
	s_branch .Lstag_s_loop
.Lstag_s_done:
	s_movk_i32 s18, 0x78
